# Fourier in-proj tile loop: LDS stage writes spread between MFMA groups, fragment reads one substep ahead, last K-slab has its own body
# speedup vs baseline: 1.0775x; 1.0006x over previous
.LBB0_1514:
	s_cmpk_lg_i32 s0, 0x780
	s_cselect_b64 s[4:5], -1, 0
	s_cmpk_eq_i32 s0, 0x780
	s_cbranch_scc1 .Lyp_last
	s_waitcnt vmcnt(5)
	v_lshl_add_u64 v[138:139], v[162:163], 0, s[0:1]
	v_add_co_u32_e32 v130, vcc, 0x2a00000, v138
	s_waitcnt vmcnt(3)
	v_lshl_add_u64 v[146:147], v[164:165], 0, s[0:1]
	v_addc_co_u32_e32 v131, vcc, 0, v139, vcc
	v_add_co_u32_e32 v134, vcc, 0x2a20000, v138
	s_waitcnt vmcnt(2)
	v_lshl_add_u64 v[150:151], v[166:167], 0, s[0:1]
	v_addc_co_u32_e32 v135, vcc, 0, v139, vcc
	v_add_co_u32_e32 v140, vcc, 0x2a40000, v138
	s_waitcnt vmcnt(1)
	v_lshl_add_u64 v[154:155], v[168:169], 0, s[0:1]
	v_addc_co_u32_e32 v141, vcc, 0, v139, vcc
	v_add_co_u32_e32 v142, vcc, 0x2a60000, v138
	s_waitcnt vmcnt(0)
	v_lshl_add_u64 v[158:159], v[170:171], 0, s[0:1]
	v_addc_co_u32_e32 v143, vcc, 0, v139, vcc
	global_load_dwordx4 v[130:133], v[130:131], off offset:128
	s_nop 0
	global_load_dwordx4 v[134:137], v[134:135], off offset:128
	s_nop 0
	global_load_dwordx4 v[138:141], v[140:141], off offset:128
	s_nop 0
	global_load_dwordx4 v[142:145], v[142:143], off offset:128
	s_nop 0
	global_load_dwordx4 v[146:149], v[146:147], off
	s_nop 0
	global_load_dwordx4 v[150:153], v[150:151], off
	s_nop 0
	global_load_dwordx4 v[154:157], v[154:155], off
	s_nop 0
	global_load_dwordx4 v[158:161], v[158:159], off
	s_and_b32 s11, s10, 1
	s_mul_i32 s15, s11, 0x12000
	v_add_u32_e32 v172, s15, v226
	v_add3_u32 v172, v172, v228, v229
	v_add_u32_e32 v173, s15, v227
	v_add3_u32 v173, v173, v228, v229
	s_xor_b32 s4, s11, 1
	s_mul_i32 s4, s4, 0x12000
	v_add_u32_e32 v218, s4, v204
	ds_read_b128 v[174:177], v172
	ds_read_b128 v[178:181], v173 offset:36864
	ds_read_b128 v[182:185], v173 offset:41472
	ds_read_b128 v[186:189], v173 offset:46080
	ds_read_b128 v[190:193], v173 offset:50688
	ds_read_b128 v[248:251], v172 offset:4608
	s_add_u32 s0, s0, 0x80
	s_addc_u32 s1, s1, 0
	s_add_i32 s10, s10, 1
	s_waitcnt lgkmcnt(4)
	v_mfma_f32_32x32x16_bf16 v[98:113], v[174:177], v[178:181], v[98:113]
	s_waitcnt lgkmcnt(3)
	v_mfma_f32_32x32x16_bf16 v[66:81], v[174:177], v[182:185], v[66:81]
	s_waitcnt lgkmcnt(2)
	v_mfma_f32_32x32x16_bf16 v[34:49], v[174:177], v[186:189], v[34:49]
	s_waitcnt lgkmcnt(1)
	v_mfma_f32_32x32x16_bf16 v[2:17], v[174:177], v[190:193], v[2:17]
	ds_read_b128 v[214:217], v172 offset:32
	ds_read_b128 v[232:235], v173 offset:36896
	ds_read_b128 v[236:239], v173 offset:41504
	ds_read_b128 v[240:243], v173 offset:46112
	ds_read_b128 v[244:247], v173 offset:50720
	s_waitcnt lgkmcnt(5)
	v_mfma_f32_32x32x16_bf16 v[114:129], v[248:251], v[178:181], v[114:129]
	v_mfma_f32_32x32x16_bf16 v[82:97], v[248:251], v[182:185], v[82:97]
	v_mfma_f32_32x32x16_bf16 v[50:65], v[248:251], v[186:189], v[50:65]
	v_mfma_f32_32x32x16_bf16 v[18:33], v[248:251], v[190:193], v[18:33]
	ds_read_b128 v[248:251], v172 offset:4640
	s_waitcnt vmcnt(7)
	ds_write_b128 v218, v[130:133]
	s_waitcnt lgkmcnt(5)
	v_mfma_f32_32x32x16_bf16 v[98:113], v[214:217], v[232:235], v[98:113]
	s_waitcnt lgkmcnt(4)
	v_mfma_f32_32x32x16_bf16 v[66:81], v[214:217], v[236:239], v[66:81]
	s_waitcnt lgkmcnt(3)
	v_mfma_f32_32x32x16_bf16 v[34:49], v[214:217], v[240:243], v[34:49]
	s_waitcnt lgkmcnt(2)
	v_mfma_f32_32x32x16_bf16 v[2:17], v[214:217], v[244:247], v[2:17]
	ds_read_b128 v[174:177], v172 offset:64
	ds_read_b128 v[178:181], v173 offset:36928
	ds_read_b128 v[182:185], v173 offset:41536
	ds_read_b128 v[186:189], v173 offset:46144
	ds_read_b128 v[190:193], v173 offset:50752
	s_waitcnt vmcnt(6)
	ds_write_b128 v218, v[134:137] offset:9216
	s_waitcnt lgkmcnt(7)
	v_mfma_f32_32x32x16_bf16 v[114:129], v[248:251], v[232:235], v[114:129]
	v_mfma_f32_32x32x16_bf16 v[82:97], v[248:251], v[236:239], v[82:97]
	v_mfma_f32_32x32x16_bf16 v[50:65], v[248:251], v[240:243], v[50:65]
	v_mfma_f32_32x32x16_bf16 v[18:33], v[248:251], v[244:247], v[18:33]
	ds_read_b128 v[248:251], v172 offset:4672
	s_waitcnt vmcnt(5)
	ds_write_b128 v218, v[138:141] offset:18432
	s_waitcnt vmcnt(4)
	ds_write_b128 v218, v[142:145] offset:27648
	s_waitcnt lgkmcnt(7)
	v_mfma_f32_32x32x16_bf16 v[98:113], v[174:177], v[178:181], v[98:113]
	s_waitcnt lgkmcnt(6)
	v_mfma_f32_32x32x16_bf16 v[66:81], v[174:177], v[182:185], v[66:81]
	s_waitcnt lgkmcnt(5)
	v_mfma_f32_32x32x16_bf16 v[34:49], v[174:177], v[186:189], v[34:49]
	s_waitcnt lgkmcnt(4)
	v_mfma_f32_32x32x16_bf16 v[2:17], v[174:177], v[190:193], v[2:17]
	ds_read_b128 v[214:217], v172 offset:96
	ds_read_b128 v[232:235], v173 offset:36960
	ds_read_b128 v[236:239], v173 offset:41568
	ds_read_b128 v[240:243], v173 offset:46176
	ds_read_b128 v[244:247], v173 offset:50784
	s_waitcnt vmcnt(3)
	ds_write_b128 v218, v[146:149] offset:36864
	s_waitcnt vmcnt(2)
	ds_write_b128 v218, v[150:153] offset:46080
	s_waitcnt lgkmcnt(9)
	v_mfma_f32_32x32x16_bf16 v[114:129], v[248:251], v[178:181], v[114:129]
	v_mfma_f32_32x32x16_bf16 v[82:97], v[248:251], v[182:185], v[82:97]
	v_mfma_f32_32x32x16_bf16 v[50:65], v[248:251], v[186:189], v[50:65]
	v_mfma_f32_32x32x16_bf16 v[18:33], v[248:251], v[190:193], v[18:33]
	ds_read_b128 v[248:251], v172 offset:4704
	s_waitcnt vmcnt(1)
	ds_write_b128 v218, v[154:157] offset:55296
	s_waitcnt vmcnt(0)
	ds_write_b128 v218, v[158:161] offset:64512
	s_waitcnt lgkmcnt(8)
	v_mfma_f32_32x32x16_bf16 v[98:113], v[214:217], v[232:235], v[98:113]
	s_waitcnt lgkmcnt(7)
	v_mfma_f32_32x32x16_bf16 v[66:81], v[214:217], v[236:239], v[66:81]
	s_waitcnt lgkmcnt(6)
	v_mfma_f32_32x32x16_bf16 v[34:49], v[214:217], v[240:243], v[34:49]
	s_waitcnt lgkmcnt(5)
	v_mfma_f32_32x32x16_bf16 v[2:17], v[214:217], v[244:247], v[2:17]
	s_waitcnt lgkmcnt(0)
	s_barrier
	v_mfma_f32_32x32x16_bf16 v[114:129], v[248:251], v[232:235], v[114:129]
	v_mfma_f32_32x32x16_bf16 v[82:97], v[248:251], v[236:239], v[82:97]
	v_mfma_f32_32x32x16_bf16 v[50:65], v[248:251], v[240:243], v[50:65]
	v_mfma_f32_32x32x16_bf16 v[18:33], v[248:251], v[244:247], v[18:33]
	s_branch .LBB0_1514
.Lyp_last:
	s_and_b32 s11, s10, 1
	s_mul_i32 s15, s11, 0x12000
	v_add_u32_e32 v172, s15, v226
	v_add3_u32 v172, v172, v228, v229
	v_add_u32_e32 v173, s15, v227
	v_add3_u32 v173, v173, v228, v229
	ds_read_b128 v[174:177], v172
	ds_read_b128 v[178:181], v173 offset:36864
	ds_read_b128 v[182:185], v173 offset:41472
	ds_read_b128 v[186:189], v173 offset:46080
	ds_read_b128 v[190:193], v173 offset:50688
	ds_read_b128 v[248:251], v172 offset:4608
	s_add_u32 s0, s0, 0x80
	s_addc_u32 s1, s1, 0
	s_add_i32 s10, s10, 1
	s_waitcnt lgkmcnt(4)
	v_mfma_f32_32x32x16_bf16 v[98:113], v[174:177], v[178:181], v[98:113]
	s_waitcnt lgkmcnt(3)
	v_mfma_f32_32x32x16_bf16 v[66:81], v[174:177], v[182:185], v[66:81]
	s_waitcnt lgkmcnt(2)
	v_mfma_f32_32x32x16_bf16 v[34:49], v[174:177], v[186:189], v[34:49]
	s_waitcnt lgkmcnt(1)
	v_mfma_f32_32x32x16_bf16 v[2:17], v[174:177], v[190:193], v[2:17]
	ds_read_b128 v[214:217], v172 offset:32
	ds_read_b128 v[232:235], v173 offset:36896
	ds_read_b128 v[236:239], v173 offset:41504
	ds_read_b128 v[240:243], v173 offset:46112
	ds_read_b128 v[244:247], v173 offset:50720
	s_waitcnt lgkmcnt(5)
	v_mfma_f32_32x32x16_bf16 v[114:129], v[248:251], v[178:181], v[114:129]
	v_mfma_f32_32x32x16_bf16 v[82:97], v[248:251], v[182:185], v[82:97]
	v_mfma_f32_32x32x16_bf16 v[50:65], v[248:251], v[186:189], v[50:65]
	v_mfma_f32_32x32x16_bf16 v[18:33], v[248:251], v[190:193], v[18:33]
	ds_read_b128 v[248:251], v172 offset:4640
	s_waitcnt lgkmcnt(4)
	v_mfma_f32_32x32x16_bf16 v[98:113], v[214:217], v[232:235], v[98:113]
	s_waitcnt lgkmcnt(3)
	v_mfma_f32_32x32x16_bf16 v[66:81], v[214:217], v[236:239], v[66:81]
	s_waitcnt lgkmcnt(2)
	v_mfma_f32_32x32x16_bf16 v[34:49], v[214:217], v[240:243], v[34:49]
	s_waitcnt lgkmcnt(1)
	v_mfma_f32_32x32x16_bf16 v[2:17], v[214:217], v[244:247], v[2:17]
	ds_read_b128 v[174:177], v172 offset:64
	ds_read_b128 v[178:181], v173 offset:36928
	ds_read_b128 v[182:185], v173 offset:41536
	ds_read_b128 v[186:189], v173 offset:46144
	ds_read_b128 v[190:193], v173 offset:50752
	s_waitcnt lgkmcnt(5)
	v_mfma_f32_32x32x16_bf16 v[114:129], v[248:251], v[232:235], v[114:129]
	v_mfma_f32_32x32x16_bf16 v[82:97], v[248:251], v[236:239], v[82:97]
	v_mfma_f32_32x32x16_bf16 v[50:65], v[248:251], v[240:243], v[50:65]
	v_mfma_f32_32x32x16_bf16 v[18:33], v[248:251], v[244:247], v[18:33]
	ds_read_b128 v[248:251], v172 offset:4672
	s_waitcnt lgkmcnt(4)
	v_mfma_f32_32x32x16_bf16 v[98:113], v[174:177], v[178:181], v[98:113]
	s_waitcnt lgkmcnt(3)
	v_mfma_f32_32x32x16_bf16 v[66:81], v[174:177], v[182:185], v[66:81]
	s_waitcnt lgkmcnt(2)
	v_mfma_f32_32x32x16_bf16 v[34:49], v[174:177], v[186:189], v[34:49]
	s_waitcnt lgkmcnt(1)
	v_mfma_f32_32x32x16_bf16 v[2:17], v[174:177], v[190:193], v[2:17]
	ds_read_b128 v[214:217], v172 offset:96
	ds_read_b128 v[232:235], v173 offset:36960
	ds_read_b128 v[236:239], v173 offset:41568
	ds_read_b128 v[240:243], v173 offset:46176
	ds_read_b128 v[244:247], v173 offset:50784
	s_waitcnt lgkmcnt(5)
	v_mfma_f32_32x32x16_bf16 v[114:129], v[248:251], v[178:181], v[114:129]
	v_mfma_f32_32x32x16_bf16 v[82:97], v[248:251], v[182:185], v[82:97]
	v_mfma_f32_32x32x16_bf16 v[50:65], v[248:251], v[186:189], v[50:65]
	v_mfma_f32_32x32x16_bf16 v[18:33], v[248:251], v[190:193], v[18:33]
	ds_read_b128 v[248:251], v172 offset:4704
	s_waitcnt lgkmcnt(4)
	v_mfma_f32_32x32x16_bf16 v[98:113], v[214:217], v[232:235], v[98:113]
	s_waitcnt lgkmcnt(3)
	v_mfma_f32_32x32x16_bf16 v[66:81], v[214:217], v[236:239], v[66:81]
	s_waitcnt lgkmcnt(2)
	v_mfma_f32_32x32x16_bf16 v[34:49], v[214:217], v[240:243], v[34:49]
	s_waitcnt lgkmcnt(1)
	v_mfma_f32_32x32x16_bf16 v[2:17], v[214:217], v[244:247], v[2:17]
	s_waitcnt lgkmcnt(0)
	s_barrier
	v_mfma_f32_32x32x16_bf16 v[114:129], v[248:251], v[232:235], v[114:129]
	v_mfma_f32_32x32x16_bf16 v[82:97], v[248:251], v[236:239], v[82:97]
	v_mfma_f32_32x32x16_bf16 v[50:65], v[248:251], v[240:243], v[50:65]
	v_mfma_f32_32x32x16_bf16 v[18:33], v[248:251], v[244:247], v[18:33]
